# v114 + the leading wave half (waves 0-3) runs the prompt item's tiles at priority 1 so the wave stagger is kept
# baseline (speedup 1.0000x reference)
; #define LAS __attribute__((address_space(3)))
; __device__ __forceinline__ int crow(int r, int hi) { return (r & 3) + 8 * (r >> 2) + 4 * hi; }
; __device__ __forceinline__ s16x4 vtr(const LAS unsigned char* p) { return __builtin_bit_cast(s16x4, __builtin_amdgcn_ds_read_tr16_b64_v4i16((LAS v4i16_t*)p)); }
; template <bool SAMPLE> ...
;     ...
;         for (int s = 0; s < 2; ++s) { pw[t][s].x = pk_bf16(p[t][8 * s + 0], p[t][8 * s + 1]); pw[t][s].y = pk_bf16(p[t][8 * s + 2], p[t][8 * s + 3]); pw[t][s].z = pk_bf16(p[t][8 * s + 4], p[t][8 * s + 5]); pw[t][s].w = pk_bf16(p[t][8 * s + 6], p[t][8 * s + 7]); }
;     }
;     lsum += __shfl_xor(lsum, 32);
;     const float denom = lsum + __builtin_amdgcn_exp2f(sk - mx);
;     if (hi == 0) wsf[r32] = 1.0f / denom;
;     __builtin_amdgcn_sched_barrier(0);
;     f32x16 o[2];
; #pragma unroll
;     for (int d0 = 0; d0 < 2; ++d0)
; #pragma unroll
;         for (int i = 0; i < 16; ++i) o[d0][i] = 0.f;
;     const int i16 = lane & 15;
;     const LAS unsigned char* vb = Vl + (4 * hi + (i16 >> 2)) * 64 + ((lane >> 4) & 1) * 32 + (i16 & 3) * 8;
; #pragma unroll
;     for (int t = 0; t < 5; ++t)
; #pragma unroll
;         for (int s = 0; s < 2; ++s) {
;             const bf16x8 pa = __builtin_bit_cast(bf16x8, pw[t][s]);
; #pragma unroll
;             for (int d0 = 0; d0 < 2; ++d0) {
;                 const s16x4 vlo = vtr(vb + d0 * vhalf + (32 * t + 16 * s) * 64), vhi = vtr(vb + d0 * vhalf + (32 * t + 16 * s + 8) * 64);
;                 const bf16x8 vf = (bf16x8){vlo[0], vlo[1], vlo[2], vlo[3], vhi[0], vhi[1], vhi[2], vhi[3]};
;                 o[d0] = __builtin_amdgcn_mfma_f32_32x32x16_bf16(pa, vf, o[d0], 0, 0, 0);
;             }
;         }
;     __builtin_amdgcn_sched_barrier(0);
;     asm volatile("s_waitcnt lgkmcnt(0)" ::: "memory");
; #pragma unroll
;     for (int i = 0; i < 16; ++i) {
;         const int qq = crow(i, hi);
;         const float rl = wsf[qq];
; #pragma unroll
;         for (int d0 = 0; d0 < 2; ++d0) ost[qq * 64 + d0 * 32 + r32] = (bf16_t)(pk_bf16(o[d0][i] * rl, 0.f) & 0xffffu);
;     }
.LBB0_458:
	s_or_b64 exec, exec, s[4:5]
	v_ashrrev_i32_e32 v127, 31, v126
	v_cvt_pk_bf16_f32 v32, v32, v33
	v_cvt_pk_bf16_f32 v33, v34, v35
	v_cvt_pk_bf16_f32 v34, v51, v50
	v_cvt_pk_bf16_f32 v35, v49, v48
	v_cvt_pk_bf16_f32 v36, v36, v37
	v_cvt_pk_bf16_f32 v37, v38, v39
	v_cvt_pk_bf16_f32 v38, v83, v82
	v_cvt_pk_bf16_f32 v39, v81, v80
	v_cvt_pk_bf16_f32 v40, v40, v41
	v_cvt_pk_bf16_f32 v41, v42, v43
	v_cvt_pk_bf16_f32 v42, v44, v45
	v_cvt_pk_bf16_f32 v43, v46, v47
	v_cvt_pk_bf16_f32 v44, v96, v97
	v_cvt_pk_bf16_f32 v45, v98, v99
	v_cvt_pk_bf16_f32 v46, v100, v101
	v_cvt_pk_bf16_f32 v47, v102, v103
	v_cvt_pk_bf16_f32 v48, v24, v25
	v_cvt_pk_bf16_f32 v49, v26, v27
	v_cvt_pk_bf16_f32 v50, v28, v29
	v_cvt_pk_bf16_f32 v51, v30, v31
	v_cvt_pk_bf16_f32 v52, v16, v17
	s_waitcnt lgkmcnt(0)
	v_cvt_pk_bf16_f32 v53, v18, v19
	v_cvt_pk_bf16_f32 v54, v20, v21
	v_cvt_pk_bf16_f32 v55, v22, v23
	v_cvt_pk_bf16_f32 v80, v8, v9
	v_cvt_pk_bf16_f32 v81, v10, v11
	v_cvt_pk_bf16_f32 v82, v12, v13
	v_cvt_pk_bf16_f32 v83, v14, v15
	v_cvt_pk_bf16_f32 v84, v0, v1
	v_cvt_pk_bf16_f32 v85, v2, v3
	v_cvt_pk_bf16_f32 v86, v4, v5
	v_cvt_pk_bf16_f32 v87, v6, v7
	v_cvt_pk_bf16_f32 v88, v88, v89
	v_cvt_pk_bf16_f32 v89, v90, v91
	v_cvt_pk_bf16_f32 v90, v92, v93
	v_cvt_pk_bf16_f32 v91, v94, v95
	v_cvt_pk_bf16_f32 v16, v56, v57
	v_cvt_pk_bf16_f32 v17, v58, v59
	v_cvt_pk_bf16_f32 v18, v60, v61
	v_cvt_pk_bf16_f32 v19, v62, v63
	v_add_u32_e32 v0, s70, v115
	v_add3_u32 v60, v0, v117, v118
	ds_read_b64_tr_b16 v[0:1], v60 offset:36864
	ds_read_b64_tr_b16 v[2:3], v60 offset:37376
	ds_read_b64_tr_b16 v[20:21], v60 offset:53248
	ds_read_b64_tr_b16 v[22:23], v60 offset:53760
	ds_read_b64_tr_b16 v[56:57], v60 offset:37888
	ds_read_b64_tr_b16 v[58:59], v60 offset:38400
	s_waitcnt lgkmcnt(4)
	v_mfma_f32_32x32x16_bf16 v[0:15], v[16:19], v[0:3], 0
	s_waitcnt lgkmcnt(2)
	v_mfma_f32_32x32x16_bf16 v[16:31], v[16:19], v[20:23], 0
	s_waitcnt lgkmcnt(0)
	v_mfma_f32_32x32x16_bf16 v[0:15], v[88:91], v[56:59], v[0:15]
	ds_read_b64_tr_b16 v[56:57], v60 offset:54272
	ds_read_b64_tr_b16 v[58:59], v60 offset:54784
	s_waitcnt lgkmcnt(0)
	v_mfma_f32_32x32x16_bf16 v[16:31], v[88:91], v[56:59], v[16:31]
	ds_read_b64_tr_b16 v[56:57], v60 offset:38912
	ds_read_b64_tr_b16 v[58:59], v60 offset:39424
	s_waitcnt lgkmcnt(0)
	v_mfma_f32_32x32x16_bf16 v[0:15], v[84:87], v[56:59], v[0:15]
	ds_read_b64_tr_b16 v[56:57], v60 offset:55296
	ds_read_b64_tr_b16 v[58:59], v60 offset:55808
	s_waitcnt lgkmcnt(0)
	v_mfma_f32_32x32x16_bf16 v[16:31], v[84:87], v[56:59], v[16:31]
	ds_read_b64_tr_b16 v[56:57], v60 offset:39936
	ds_read_b64_tr_b16 v[58:59], v60 offset:40448
	s_waitcnt lgkmcnt(0)
	v_mfma_f32_32x32x16_bf16 v[0:15], v[80:83], v[56:59], v[0:15]
	ds_read_b64_tr_b16 v[56:57], v60 offset:56320
	ds_read_b64_tr_b16 v[58:59], v60 offset:56832
	s_waitcnt lgkmcnt(0)
	v_mfma_f32_32x32x16_bf16 v[16:31], v[80:83], v[56:59], v[16:31]
	ds_read_b64_tr_b16 v[56:57], v60 offset:40960
	ds_read_b64_tr_b16 v[58:59], v60 offset:41472
	s_waitcnt lgkmcnt(0)
	v_mfma_f32_32x32x16_bf16 v[0:15], v[52:55], v[56:59], v[0:15]
	ds_read_b64_tr_b16 v[56:57], v60 offset:57344
	ds_read_b64_tr_b16 v[58:59], v60 offset:57856
	s_waitcnt lgkmcnt(0)
	v_mfma_f32_32x32x16_bf16 v[16:31], v[52:55], v[56:59], v[16:31]
	ds_read_b64_tr_b16 v[52:53], v60 offset:41984
	ds_read_b64_tr_b16 v[54:55], v60 offset:42496
	s_waitcnt lgkmcnt(0)
	v_mfma_f32_32x32x16_bf16 v[0:15], v[48:51], v[52:55], v[0:15]
	ds_read_b64_tr_b16 v[52:53], v60 offset:58368
	ds_read_b64_tr_b16 v[54:55], v60 offset:58880
	s_waitcnt lgkmcnt(0)
	v_mfma_f32_32x32x16_bf16 v[16:31], v[48:51], v[52:55], v[16:31]
	ds_read_b64_tr_b16 v[48:49], v60 offset:43008
	ds_read_b64_tr_b16 v[50:51], v60 offset:43520
	s_waitcnt lgkmcnt(0)
	v_mfma_f32_32x32x16_bf16 v[0:15], v[44:47], v[48:51], v[0:15]
	ds_read_b64_tr_b16 v[48:49], v60 offset:59392
	ds_read_b64_tr_b16 v[50:51], v60 offset:59904
	s_waitcnt lgkmcnt(0)
	v_mfma_f32_32x32x16_bf16 v[16:31], v[44:47], v[48:51], v[16:31]
	ds_read_b64_tr_b16 v[44:45], v60 offset:44032
	ds_read_b64_tr_b16 v[46:47], v60 offset:44544
	s_waitcnt lgkmcnt(0)
	v_mfma_f32_32x32x16_bf16 v[0:15], v[40:43], v[44:47], v[0:15]
	ds_read_b64_tr_b16 v[44:45], v60 offset:60416
	ds_read_b64_tr_b16 v[46:47], v60 offset:60928
	s_waitcnt lgkmcnt(0)
	v_mfma_f32_32x32x16_bf16 v[16:31], v[40:43], v[44:47], v[16:31]
	ds_read_b64_tr_b16 v[40:41], v60 offset:45056
	ds_read_b64_tr_b16 v[42:43], v60 offset:45568
	s_waitcnt lgkmcnt(0)
	v_mfma_f32_32x32x16_bf16 v[0:15], v[36:39], v[40:43], v[0:15]
	ds_read_b64_tr_b16 v[40:41], v60 offset:61440
	ds_read_b64_tr_b16 v[42:43], v60 offset:61952
	s_waitcnt lgkmcnt(0)
	v_mfma_f32_32x32x16_bf16 v[16:31], v[36:39], v[40:43], v[16:31]
	ds_read_b64_tr_b16 v[36:37], v60 offset:46080
	ds_read_b64_tr_b16 v[38:39], v60 offset:46592
	s_waitcnt lgkmcnt(0)
	v_mfma_f32_32x32x16_bf16 v[0:15], v[32:35], v[36:39], v[0:15]
	ds_read_b64_tr_b16 v[36:37], v60 offset:62464
	ds_read_b64_tr_b16 v[38:39], v60 offset:62976
	s_waitcnt lgkmcnt(0)
	v_mfma_f32_32x32x16_bf16 v[16:31], v[32:35], v[36:39], v[16:31]
	s_waitcnt lgkmcnt(0)
	ds_read_b128 v[32:35], v112
	ds_read_b128 v[36:39], v112 offset:32
	v_mov_b32_e32 v125, v173
	s_add_i32 s71, s71, s42
	s_cmpk_gt_i32 s71, 0xff
	s_waitcnt lgkmcnt(1)
	s_nop 1
	v_mul_f32_e32 v0, v0, v32
	s_nop 2
	v_mul_f32_e32 v16, v16, v32
	v_cvt_pk_bf16_f32 v0, v0, s0
	v_cvt_pk_bf16_f32 v16, v16, s0
	ds_write_b16 v116, v0
	ds_write_b16 v116, v16 offset:64
	v_mul_f32_e32 v0, v1, v33
	v_cvt_pk_bf16_f32 v0, v0, s0
	ds_write_b16 v119, v0
	v_mul_f32_e32 v0, v17, v33
	v_cvt_pk_bf16_f32 v0, v0, s0
	ds_write_b16 v119, v0 offset:64
	v_mul_f32_e32 v0, v2, v34
	v_cvt_pk_bf16_f32 v0, v0, s0
	ds_write_b16 v120, v0
	v_mul_f32_e32 v0, v18, v34
	v_cvt_pk_bf16_f32 v0, v0, s0
	ds_write_b16 v120, v0 offset:64
	v_mul_f32_e32 v0, v3, v35
	v_cvt_pk_bf16_f32 v0, v0, s0
	ds_write_b16 v121, v0
	v_mul_f32_e32 v0, v19, v35
	v_cvt_pk_bf16_f32 v0, v0, s0
	ds_write_b16 v121, v0 offset:64
	s_waitcnt lgkmcnt(8)
; #define LAS __attribute__((address_space(3)))
; __device__ __forceinline__ u32x4 pack8(const float (&f)[8]) { u32x4 w; w.x = pk_bf16(f[0], f[1]); w.y = pk_bf16(f[2], f[3]); w.z = pk_bf16(f[4], f[5]); w.w = pk_bf16(f[6], f[7]); return w; }
; __device__ __forceinline__ int crow(int r, int hi) { return (r & 3) + 8 * (r >> 2) + 4 * hi; }
; template <bool SAMPLE> ...
;     ...
; #pragma unroll
;     for (int i = 0; i < 16; ++i) {
;         const int qq = crow(i, hi);
;         const float rl = wsf[qq];
; #pragma unroll
;         for (int d0 = 0; d0 < 2; ++d0) ost[qq * 64 + d0 * 32 + r32] = (bf16_t)(pk_bf16(o[d0][i] * rl, 0.f) & 0xffffu);
;     }
;     asm volatile("s_waitcnt lgkmcnt(0)" ::: "memory");
; #pragma unroll
;     for (int it4 = 0; it4 < 4; ++it4) {
;         const int qq = it4 * 8 + (lane >> 3), ch = lane & 7;
;         const int orow = SAMPLE ? row0 + (qq & 7) : row0 + qq;
;         const int ohead = SAMPLE ? head0 + (qq >> 3) : head0;
;         const u32x4 ow = *(const LAS u32x4*)(ost + qq * 64 + ch * 8);
;         float of[8], zf[8], yv[8];
;         unpack8(ow, of); unpack8(zw[it4], zf);
; #pragma unroll
;         for (int k = 0; k < 8; ++k) yv[k] = of[k] * zf[k];
;         *(u32x4*)(Y + (size_t)orow * D + 512 + ohead * 64 + ch * 8) = pack8(yv);
;     }
; __device__ __forceinline__ void p_mixer(const Args& a, int l, LAS unsigned char* lds, int tid, int lane, int wave, int bid, int G) {
;     ...
;             for (int it = bid; it < N_AP; it += G) { asm volatile("" : "+v"(tid)); lane = tid & 63; attn_prompt_item(a, l, it, lds, tid, lane, wave); }
	v_mul_f32_e32 v0, v4, v36
	v_cvt_pk_bf16_f32 v0, v0, s0
	ds_write_b16 v122, v0
	v_mul_f32_e32 v0, v20, v36
	v_cvt_pk_bf16_f32 v0, v0, s0
	ds_write_b16 v122, v0 offset:64
	v_mul_f32_e32 v0, v5, v37
	v_cvt_pk_bf16_f32 v0, v0, s0
	ds_write_b16 v123, v0
	v_mul_f32_e32 v0, v21, v37
	v_cvt_pk_bf16_f32 v0, v0, s0
	ds_write_b16 v123, v0 offset:64
	v_mul_f32_e32 v0, v6, v38
	v_cvt_pk_bf16_f32 v0, v0, s0
	ds_write_b16 v135, v0
	v_mul_f32_e32 v0, v22, v38
	v_cvt_pk_bf16_f32 v0, v0, s0
	ds_write_b16 v135, v0 offset:64
	v_mul_f32_e32 v0, v7, v39
	v_cvt_pk_bf16_f32 v0, v0, s0
	ds_write_b16 v134, v0
	ds_read_b128 v[0:3], v112 offset:64
	v_mul_f32_e32 v4, v23, v39
	v_cvt_pk_bf16_f32 v4, v4, s0
	ds_write_b16 v134, v4 offset:64
	ds_read_b128 v[4:7], v112 offset:96
	s_waitcnt lgkmcnt(2)
	v_mul_f32_e32 v8, v8, v0
	v_mul_f32_e32 v0, v24, v0
	v_cvt_pk_bf16_f32 v0, v0, s0
	ds_write_b16 v136, v0 offset:64
	v_mul_f32_e32 v0, v9, v1
	v_cvt_pk_bf16_f32 v0, v0, s0
	ds_write_b16 v137, v0
	v_mul_f32_e32 v0, v25, v1
	v_cvt_pk_bf16_f32 v0, v0, s0
	ds_write_b16 v137, v0 offset:64
	v_mul_f32_e32 v0, v10, v2
	v_cvt_pk_bf16_f32 v0, v0, s0
	ds_write_b16 v138, v0
	v_mul_f32_e32 v0, v26, v2
	v_cvt_pk_bf16_f32 v0, v0, s0
	ds_write_b16 v138, v0 offset:64
	v_mul_f32_e32 v0, v11, v3
	v_cvt_pk_bf16_f32 v0, v0, s0
	ds_write_b16 v139, v0
	v_mul_f32_e32 v0, v27, v3
	v_cvt_pk_bf16_f32 v0, v0, s0
	ds_write_b16 v139, v0 offset:64
	s_waitcnt lgkmcnt(7)
	v_mul_f32_e32 v0, v12, v4
	v_cvt_pk_bf16_f32 v0, v0, s0
	ds_write_b16 v140, v0
	v_mul_f32_e32 v0, v28, v4
	v_cvt_pk_bf16_f32 v0, v0, s0
	ds_write_b16 v140, v0 offset:64
	v_mul_f32_e32 v0, v13, v5
	v_cvt_pk_bf16_f32 v0, v0, s0
	ds_write_b16 v141, v0
	v_mul_f32_e32 v0, v29, v5
	v_cvt_pk_bf16_f32 v0, v0, s0
	ds_write_b16 v141, v0 offset:64
	v_mul_f32_e32 v0, v14, v6
	v_cvt_pk_bf16_f32 v0, v0, s0
	ds_write_b16 v142, v0
	v_mul_f32_e32 v0, v30, v6
	v_cvt_pk_bf16_f32 v0, v0, s0
	ds_write_b16 v142, v0 offset:64
	v_mul_f32_e32 v0, v15, v7
	v_cvt_pk_bf16_f32 v0, v0, s0
	ds_write_b16 v143, v0
	v_mul_f32_e32 v0, v31, v7
	v_cvt_pk_bf16_f32 v8, v8, s0
	v_cvt_pk_bf16_f32 v0, v0, s0
	ds_write_b16 v136, v8
	ds_write_b16 v143, v0 offset:64
	s_waitcnt lgkmcnt(0)
	ds_read_b128 v[0:3], v144
	ds_read_b128 v[4:7], v145
	v_lshlrev_b32_e32 v10, 16, v76
	v_and_b32_e32 v11, 0xffff0000, v76
	v_lshlrev_b32_e32 v12, 16, v78
	s_waitcnt lgkmcnt(1)
	v_lshlrev_b32_e32 v8, 16, v0
	v_and_b32_e32 v9, 0xffff0000, v0
	v_pk_mul_f32 v[8:9], v[10:11], v[8:9]
	v_lshlrev_b32_e32 v0, 16, v1
	v_and_b32_e32 v1, 0xffff0000, v1
	v_lshlrev_b32_e32 v10, 16, v77
	v_and_b32_e32 v11, 0xffff0000, v77
	v_pk_mul_f32 v[10:11], v[10:11], v[0:1]
	v_lshlrev_b32_e32 v0, 16, v2
	v_and_b32_e32 v1, 0xffff0000, v2
	v_and_b32_e32 v13, 0xffff0000, v78
	v_pk_mul_f32 v[12:13], v[12:13], v[0:1]
	v_lshlrev_b32_e32 v0, 16, v3
	v_and_b32_e32 v1, 0xffff0000, v3
	v_lshlrev_b32_e32 v2, 16, v79
	v_and_b32_e32 v3, 0xffff0000, v79
	v_pk_mul_f32 v[14:15], v[2:3], v[0:1]
	v_cvt_pk_bf16_f32 v0, v8, v9
	v_lshlrev_b64 v[8:9], 11, v[126:127]
	v_lshl_add_u64 v[8:9], s[46:47], 0, v[8:9]
	v_lshl_add_u64 v[8:9], v[8:9], 0, s[52:53]
	v_cvt_pk_bf16_f32 v1, v10, v11
	v_cvt_pk_bf16_f32 v2, v12, v13
	v_cvt_pk_bf16_f32 v3, v14, v15
	v_lshl_add_u64 v[8:9], v[8:9], 0, v[124:125]
	global_store_dwordx4 v[8:9], v[0:3], off offset:1024
	v_lshlrev_b32_e32 v8, 16, v74
	v_and_b32_e32 v9, 0xffff0000, v74
	s_waitcnt lgkmcnt(0)
	v_lshlrev_b32_e32 v0, 16, v4
	v_and_b32_e32 v1, 0xffff0000, v4
	v_lshlrev_b32_e32 v2, 16, v72
	v_and_b32_e32 v3, 0xffff0000, v72
	v_pk_mul_f32 v[0:1], v[2:3], v[0:1]
	v_lshlrev_b32_e32 v2, 16, v5
	v_and_b32_e32 v3, 0xffff0000, v5
	v_lshlrev_b32_e32 v4, 16, v73
	v_and_b32_e32 v5, 0xffff0000, v73
	v_pk_mul_f32 v[2:3], v[4:5], v[2:3]
	v_lshlrev_b32_e32 v4, 16, v6
	v_and_b32_e32 v5, 0xffff0000, v6
	v_pk_mul_f32 v[4:5], v[8:9], v[4:5]
	v_lshlrev_b32_e32 v6, 16, v7
	v_and_b32_e32 v7, 0xffff0000, v7
	v_lshlrev_b32_e32 v8, 16, v75
	v_and_b32_e32 v9, 0xffff0000, v75
	v_pk_mul_f32 v[6:7], v[8:9], v[6:7]
	v_or_b32_e32 v8, s73, v114
	v_ashrrev_i32_e32 v9, 31, v8
	v_cvt_pk_bf16_f32 v0, v0, v1
	v_cvt_pk_bf16_f32 v1, v2, v3
	v_cvt_pk_bf16_f32 v2, v4, v5
	v_lshlrev_b64 v[4:5], 11, v[8:9]
	v_cvt_pk_bf16_f32 v3, v6, v7
	v_lshl_add_u64 v[8:9], s[46:47], 0, v[4:5]
	ds_read_b128 v[4:7], v106
	v_lshl_add_u64 v[8:9], v[8:9], 0, s[52:53]
	v_lshl_add_u64 v[8:9], v[8:9], 0, v[124:125]
	global_store_dwordx4 v[8:9], v[0:3], off offset:1024
	ds_read_b128 v[0:3], v107
	s_waitcnt lgkmcnt(1)
	v_lshlrev_b32_e32 v8, 16, v4
	v_and_b32_e32 v9, 0xffff0000, v4
	v_lshlrev_b32_e32 v10, 16, v68
	v_and_b32_e32 v11, 0xffff0000, v68
	v_pk_mul_f32 v[8:9], v[10:11], v[8:9]
	v_lshlrev_b32_e32 v4, 16, v5
	v_and_b32_e32 v5, 0xffff0000, v5
	v_lshlrev_b32_e32 v10, 16, v69
	v_and_b32_e32 v11, 0xffff0000, v69
	v_pk_mul_f32 v[10:11], v[10:11], v[4:5]
	v_lshlrev_b32_e32 v4, 16, v6
	v_and_b32_e32 v5, 0xffff0000, v6
	v_lshlrev_b32_e32 v12, 16, v70
	v_and_b32_e32 v13, 0xffff0000, v70
	v_or_b32_e32 v16, s73, v104
	v_pk_mul_f32 v[12:13], v[12:13], v[4:5]
	v_lshlrev_b32_e32 v4, 16, v7
	v_and_b32_e32 v5, 0xffff0000, v7
	v_lshlrev_b32_e32 v6, 16, v71
	v_and_b32_e32 v7, 0xffff0000, v71
	v_ashrrev_i32_e32 v17, 31, v16
	v_pk_mul_f32 v[14:15], v[6:7], v[4:5]
	v_cvt_pk_bf16_f32 v4, v8, v9
	v_lshlrev_b64 v[8:9], 11, v[16:17]
	v_lshl_add_u64 v[8:9], s[46:47], 0, v[8:9]
	v_lshl_add_u64 v[8:9], v[8:9], 0, s[52:53]
	v_cvt_pk_bf16_f32 v5, v10, v11
	v_cvt_pk_bf16_f32 v6, v12, v13
	v_cvt_pk_bf16_f32 v7, v14, v15
	v_lshl_add_u64 v[8:9], v[8:9], 0, v[124:125]
	global_store_dwordx4 v[8:9], v[4:7], off offset:1024
	v_lshlrev_b32_e32 v8, 16, v66
	v_and_b32_e32 v9, 0xffff0000, v66
	s_waitcnt lgkmcnt(0)
	v_lshlrev_b32_e32 v4, 16, v0
	v_and_b32_e32 v5, 0xffff0000, v0
	v_lshlrev_b32_e32 v6, 16, v64
	v_and_b32_e32 v7, 0xffff0000, v64
	v_pk_mul_f32 v[4:5], v[6:7], v[4:5]
	v_lshlrev_b32_e32 v0, 16, v1
	v_and_b32_e32 v1, 0xffff0000, v1
	v_lshlrev_b32_e32 v6, 16, v65
	v_and_b32_e32 v7, 0xffff0000, v65
	v_pk_mul_f32 v[6:7], v[6:7], v[0:1]
	v_lshlrev_b32_e32 v0, 16, v2
	v_and_b32_e32 v1, 0xffff0000, v2
	v_or_b32_e32 v12, s73, v105
	v_pk_mul_f32 v[8:9], v[8:9], v[0:1]
	v_lshlrev_b32_e32 v0, 16, v3
	v_and_b32_e32 v1, 0xffff0000, v3
	v_lshlrev_b32_e32 v2, 16, v67
	v_and_b32_e32 v3, 0xffff0000, v67
	v_ashrrev_i32_e32 v13, 31, v12
	v_pk_mul_f32 v[10:11], v[2:3], v[0:1]
	v_cvt_pk_bf16_f32 v0, v4, v5
	v_lshlrev_b64 v[4:5], 11, v[12:13]
	v_lshl_add_u64 v[4:5], s[46:47], 0, v[4:5]
	v_lshl_add_u64 v[4:5], v[4:5], 0, s[52:53]
	v_cvt_pk_bf16_f32 v1, v6, v7
	v_cvt_pk_bf16_f32 v2, v8, v9
	v_cvt_pk_bf16_f32 v3, v10, v11
	v_lshl_add_u64 v[4:5], v[4:5], 0, v[124:125]
	global_store_dwordx4 v[4:5], v[0:3], off offset:1024
	s_waitcnt lgkmcnt(0)
	s_mov_b64 s[26:27], 0x1000
	s_setprio 0
	s_barrier
	s_cbranch_scc1 .LBB0_444

; __device__ __forceinline__ void p_mixer(const Args& a, int l, LAS unsigned char* lds, int tid, int lane, int wave, int bid, int G) {
;     ...
;         if (!prompt_done && (!qfirst || pulled >= 1 || queue_empty)) {
; #pragma unroll 1
;             for (int it = bid; it < N_AP; it += G) { asm volatile("" : "+v"(tid)); lane = tid & 63; attn_prompt_item(a, l, it, lds, tid, lane, wave); }
.Lstg_skip:
	s_cmpk_lt_u32 s0, 0x100
	s_cbranch_scc0 .Lpr2_skip
	s_setprio 1
